# GEMM K-loop: every 8-byte instruction (MFMA, ds_read, LDS-DMA) padded to 8-byte alignment with 24 s_nop 0, on v056
# speedup vs baseline: 1.0039x; 1.0039x over previous
.LBB0_141:
	s_add_i32 s72, s40, 2
	s_nop 0
	s_add_u32 s68, s0, 0x80
	s_addc_u32 s41, s1, 0
	s_nop 0
	s_add_i32 s73, 0, 0x10000
	v_add_u32_e32 v140, s73, v183
	s_nop 0
	ds_read_b128 v[128:131], v140
	ds_read_b128 v[132:135], v140 offset:1024
	ds_read_b128 v[136:139], v140 offset:2048
	ds_read_b128 v[140:143], v140 offset:3072
	s_cmp_eq_u32 s10, s40
	s_cselect_b32 s40, s64, s68
	s_cselect_b32 s41, s65, s41
	s_cselect_b32 s69, s67, s71
	s_cselect_b32 s68, s66, s70
	s_nop 0
	v_lshl_add_u64 v[176:177], s[0:1], 0, v[192:193]
	s_add_i32 m0, s76, 0xc000
	ds_read_b128 v[144:147], v239
	ds_read_b128 v[148:151], v239 offset:1024
	ds_read_b128 v[152:155], v239 offset:2048
	ds_read_b128 v[156:159], v239 offset:3072
	ds_read_b128 v[160:163], v239 offset:4096
	ds_read_b128 v[164:167], v239 offset:5120
	ds_read_b128 v[168:171], v239 offset:6144
	ds_read_b128 v[172:175], v239 offset:7168
	global_load_lds_dwordx4 v[176:177], off
	v_lshl_add_u64 v[176:177], s[0:1], 0, v[194:195]
	s_add_i32 m0, s76, 0xe000
	s_nop 0
	s_nop 0
	global_load_lds_dwordx4 v[176:177], off
	s_waitcnt lgkmcnt(8)
	s_barrier
	s_waitcnt lgkmcnt(0)
	s_setprio 1
	s_waitcnt lgkmcnt(0)
	s_nop 0
	v_mfma_f32_16x16x32_bf16 v[124:127], v[128:131], v[144:147], v[124:127]
	v_mfma_f32_16x16x32_bf16 v[116:119], v[136:139], v[144:147], v[116:119]
	v_mfma_f32_16x16x32_bf16 v[108:111], v[128:131], v[152:155], v[108:111]
	v_mfma_f32_16x16x32_bf16 v[100:103], v[136:139], v[152:155], v[100:103]
	v_mfma_f32_16x16x32_bf16 v[92:95], v[128:131], v[160:163], v[92:95]
	v_mfma_f32_16x16x32_bf16 v[84:87], v[136:139], v[160:163], v[84:87]
	v_mfma_f32_16x16x32_bf16 v[76:79], v[128:131], v[168:171], v[76:79]
	v_mfma_f32_16x16x32_bf16 v[68:71], v[136:139], v[168:171], v[68:71]
	v_mfma_f32_16x16x32_bf16 v[124:127], v[132:135], v[148:151], v[124:127]
	v_mfma_f32_16x16x32_bf16 v[116:119], v[140:143], v[148:151], v[116:119]
	v_mfma_f32_16x16x32_bf16 v[108:111], v[132:135], v[156:159], v[108:111]
	v_mfma_f32_16x16x32_bf16 v[100:103], v[140:143], v[156:159], v[100:103]
	v_mfma_f32_16x16x32_bf16 v[92:95], v[132:135], v[164:167], v[92:95]
	v_mfma_f32_16x16x32_bf16 v[84:87], v[140:143], v[164:167], v[84:87]
	v_mfma_f32_16x16x32_bf16 v[76:79], v[132:135], v[172:175], v[76:79]
	v_mfma_f32_16x16x32_bf16 v[68:71], v[140:143], v[172:175], v[68:71]
	s_setprio 0
	s_barrier
	s_add_i32 s80, 0, 0x14000
	s_add_i32 s73, s73, s33
	v_add_u32_e32 v204, s80, v183
	v_lshl_add_u64 v[208:209], s[68:69], 0, v[186:187]
	s_mov_b32 m0, s73
	s_nop 0
	ds_read_b128 v[176:179], v204
	ds_read_b128 v[196:199], v204 offset:1024
	ds_read_b128 v[200:203], v204 offset:2048
	ds_read_b128 v[204:207], v204 offset:3072
	global_load_lds_dwordx4 v[208:209], off
	v_lshl_add_u64 v[210:211], s[68:69], 0, v[190:191]
	s_add_i32 m0, s73, 0x2000
	s_nop 0
	s_nop 0
	global_load_lds_dwordx4 v[210:211], off
	s_barrier
	s_waitcnt lgkmcnt(0)
	s_setprio 1
	s_waitcnt lgkmcnt(0)
	v_mfma_f32_16x16x32_bf16 v[120:123], v[176:179], v[144:147], v[120:123]
	v_mfma_f32_16x16x32_bf16 v[112:115], v[200:203], v[144:147], v[112:115]
	v_mfma_f32_16x16x32_bf16 v[104:107], v[176:179], v[152:155], v[104:107]
	v_mfma_f32_16x16x32_bf16 v[96:99], v[200:203], v[152:155], v[96:99]
	v_mfma_f32_16x16x32_bf16 v[88:91], v[176:179], v[160:163], v[88:91]
	v_mfma_f32_16x16x32_bf16 v[80:83], v[200:203], v[160:163], v[80:83]
	v_mfma_f32_16x16x32_bf16 v[72:75], v[176:179], v[168:171], v[72:75]
	v_mfma_f32_16x16x32_bf16 v[64:67], v[200:203], v[168:171], v[64:67]
	v_mfma_f32_16x16x32_bf16 v[120:123], v[196:199], v[148:151], v[120:123]
	v_mfma_f32_16x16x32_bf16 v[112:115], v[204:207], v[148:151], v[112:115]
	v_mfma_f32_16x16x32_bf16 v[104:107], v[196:199], v[156:159], v[104:107]
	v_mfma_f32_16x16x32_bf16 v[96:99], v[204:207], v[156:159], v[96:99]
	v_mfma_f32_16x16x32_bf16 v[88:91], v[196:199], v[164:167], v[88:91]
	v_mfma_f32_16x16x32_bf16 v[80:83], v[204:207], v[164:167], v[80:83]
	v_mfma_f32_16x16x32_bf16 v[72:75], v[196:199], v[172:175], v[72:75]
	v_mfma_f32_16x16x32_bf16 v[64:67], v[204:207], v[172:175], v[64:67]
	s_setprio 0
	s_mov_b32 m0, s76
	v_lshl_add_u64 v[212:213], s[40:41], 0, v[184:185]
	s_barrier
	s_nop 0
	ds_read_b128 v[144:147], v239 offset:16384
	ds_read_b128 v[148:151], v239 offset:17408
	ds_read_b128 v[152:155], v239 offset:18432
	ds_read_b128 v[156:159], v239 offset:19456
	ds_read_b128 v[160:163], v239 offset:20480
	ds_read_b128 v[164:167], v239 offset:21504
	ds_read_b128 v[168:171], v239 offset:22528
	ds_read_b128 v[172:175], v239 offset:23552
	global_load_lds_dwordx4 v[212:213], off
	v_lshl_add_u64 v[214:215], s[40:41], 0, v[188:189]
	s_mov_b32 m0, s4
	s_nop 0
	global_load_lds_dwordx4 v[214:215], off
	s_barrier
	s_waitcnt lgkmcnt(0)
	s_setprio 1
	s_waitcnt lgkmcnt(0)
	v_mfma_f32_16x16x32_bf16 v[60:63], v[128:131], v[144:147], v[60:63]
	v_mfma_f32_16x16x32_bf16 v[52:55], v[136:139], v[144:147], v[52:55]
	v_mfma_f32_16x16x32_bf16 v[44:47], v[128:131], v[152:155], v[44:47]
	v_mfma_f32_16x16x32_bf16 v[36:39], v[136:139], v[152:155], v[36:39]
	v_mfma_f32_16x16x32_bf16 v[28:31], v[128:131], v[160:163], v[28:31]
	v_mfma_f32_16x16x32_bf16 v[20:23], v[136:139], v[160:163], v[20:23]
	v_mfma_f32_16x16x32_bf16 v[12:15], v[128:131], v[168:171], v[12:15]
	v_mfma_f32_16x16x32_bf16 v[4:7], v[136:139], v[168:171], v[4:7]
	v_mfma_f32_16x16x32_bf16 v[60:63], v[132:135], v[148:151], v[60:63]
	v_mfma_f32_16x16x32_bf16 v[52:55], v[140:143], v[148:151], v[52:55]
	v_mfma_f32_16x16x32_bf16 v[44:47], v[132:135], v[156:159], v[44:47]
	v_mfma_f32_16x16x32_bf16 v[36:39], v[140:143], v[156:159], v[36:39]
	v_mfma_f32_16x16x32_bf16 v[28:31], v[132:135], v[164:167], v[28:31]
	v_mfma_f32_16x16x32_bf16 v[20:23], v[140:143], v[164:167], v[20:23]
	v_mfma_f32_16x16x32_bf16 v[12:15], v[132:135], v[172:175], v[12:15]
	v_mfma_f32_16x16x32_bf16 v[4:7], v[140:143], v[172:175], v[4:7]
	s_setprio 0
	s_barrier
	s_add_u32 s68, s68, s98
	s_addc_u32 s69, s69, 0
	s_add_i32 s73, s80, s33
	s_nop 0
	v_lshl_add_u64 v[216:217], s[68:69], 0, v[186:187]
	s_mov_b32 m0, s73
	s_nop 0
	v_lshl_add_u64 v[218:219], s[68:69], 0, v[190:191]
	global_load_lds_dwordx4 v[216:217], off
	s_add_i32 m0, s73, 0x2000
	s_nop 0
	s_nop 0
	global_load_lds_dwordx4 v[218:219], off
	s_waitcnt vmcnt(6)
	s_barrier
	s_setprio 1
	s_nop 0
	v_mfma_f32_16x16x32_bf16 v[56:59], v[176:179], v[144:147], v[56:59]
	v_mfma_f32_16x16x32_bf16 v[48:51], v[200:203], v[144:147], v[48:51]
	v_mfma_f32_16x16x32_bf16 v[40:43], v[176:179], v[152:155], v[40:43]
	v_mfma_f32_16x16x32_bf16 v[32:35], v[200:203], v[152:155], v[32:35]
	v_mfma_f32_16x16x32_bf16 v[24:27], v[176:179], v[160:163], v[24:27]
	v_mfma_f32_16x16x32_bf16 v[16:19], v[200:203], v[160:163], v[16:19]
	v_mfma_f32_16x16x32_bf16 v[8:11], v[176:179], v[168:171], v[8:11]
	v_mfma_f32_16x16x32_bf16 v[0:3], v[200:203], v[168:171], v[0:3]
	v_mfma_f32_16x16x32_bf16 v[56:59], v[196:199], v[148:151], v[56:59]
	v_mfma_f32_16x16x32_bf16 v[48:51], v[204:207], v[148:151], v[48:51]
	v_mfma_f32_16x16x32_bf16 v[40:43], v[196:199], v[156:159], v[40:43]
	v_mfma_f32_16x16x32_bf16 v[32:35], v[204:207], v[156:159], v[32:35]
	v_mfma_f32_16x16x32_bf16 v[24:27], v[196:199], v[164:167], v[24:27]
	v_mfma_f32_16x16x32_bf16 v[16:19], v[204:207], v[164:167], v[16:19]
	v_mfma_f32_16x16x32_bf16 v[8:11], v[196:199], v[172:175], v[8:11]
	v_mfma_f32_16x16x32_bf16 v[0:3], v[204:207], v[172:175], v[0:3]
	s_setprio 0
	s_nop 0
	s_add_i32 s68, 0, 0x18000
	v_add_u32_e32 v140, s68, v183
	s_barrier
	ds_read_b128 v[128:131], v140
	ds_read_b128 v[132:135], v140 offset:1024
	ds_read_b128 v[136:139], v140 offset:2048
	ds_read_b128 v[140:143], v140 offset:3072
	s_add_u32 s40, s40, s98
	s_addc_u32 s41, s41, 0
	s_mov_b32 m0, s5
	s_nop 0
	v_lshl_add_u64 v[176:177], s[40:41], 0, v[184:185]
	ds_read_b128 v[144:147], v239 offset:32768
	ds_read_b128 v[148:151], v239 offset:33792
	ds_read_b128 v[152:155], v239 offset:34816
	ds_read_b128 v[156:159], v239 offset:35840
	ds_read_b128 v[160:163], v239 offset:36864
	ds_read_b128 v[164:167], v239 offset:37888
	ds_read_b128 v[168:171], v239 offset:38912
	ds_read_b128 v[172:175], v239 offset:39936
	global_load_lds_dwordx4 v[176:177], off
	v_lshl_add_u64 v[176:177], s[40:41], 0, v[188:189]
	s_mov_b32 m0, s6
	s_nop 0
	global_load_lds_dwordx4 v[176:177], off
	s_waitcnt lgkmcnt(8)
	s_barrier
	s_waitcnt lgkmcnt(0)
	s_setprio 1
	s_waitcnt lgkmcnt(0)
	s_nop 0
	v_mfma_f32_16x16x32_bf16 v[124:127], v[128:131], v[144:147], v[124:127]
	v_mfma_f32_16x16x32_bf16 v[116:119], v[136:139], v[144:147], v[116:119]
	v_mfma_f32_16x16x32_bf16 v[108:111], v[128:131], v[152:155], v[108:111]
	v_mfma_f32_16x16x32_bf16 v[100:103], v[136:139], v[152:155], v[100:103]
	v_mfma_f32_16x16x32_bf16 v[92:95], v[128:131], v[160:163], v[92:95]
	v_mfma_f32_16x16x32_bf16 v[84:87], v[136:139], v[160:163], v[84:87]
	v_mfma_f32_16x16x32_bf16 v[76:79], v[128:131], v[168:171], v[76:79]
	v_mfma_f32_16x16x32_bf16 v[68:71], v[136:139], v[168:171], v[68:71]
	v_mfma_f32_16x16x32_bf16 v[124:127], v[132:135], v[148:151], v[124:127]
	v_mfma_f32_16x16x32_bf16 v[116:119], v[140:143], v[148:151], v[116:119]
	v_mfma_f32_16x16x32_bf16 v[108:111], v[132:135], v[156:159], v[108:111]
	v_mfma_f32_16x16x32_bf16 v[100:103], v[140:143], v[156:159], v[100:103]
	v_mfma_f32_16x16x32_bf16 v[92:95], v[132:135], v[164:167], v[92:95]
	v_mfma_f32_16x16x32_bf16 v[84:87], v[140:143], v[164:167], v[84:87]
	v_mfma_f32_16x16x32_bf16 v[76:79], v[132:135], v[172:175], v[76:79]
	v_mfma_f32_16x16x32_bf16 v[68:71], v[140:143], v[172:175], v[68:71]
	s_setprio 0
	s_barrier
	s_add_i32 s40, 0, 0x1c000
	s_add_i32 s41, s68, s33
	v_add_u32_e32 v204, s40, v183
	v_lshl_add_u64 v[208:209], v[208:209], 0, s[96:97]
	s_mov_b32 m0, s41
	s_nop 0
	ds_read_b128 v[176:179], v204
	ds_read_b128 v[196:199], v204 offset:1024
	ds_read_b128 v[200:203], v204 offset:2048
	ds_read_b128 v[204:207], v204 offset:3072
	global_load_lds_dwordx4 v[208:209], off
	v_lshl_add_u64 v[208:209], v[210:211], 0, s[96:97]
	s_add_i32 m0, s41, 0x2000
	s_nop 0
	s_nop 0
	global_load_lds_dwordx4 v[208:209], off
	s_barrier
	s_waitcnt lgkmcnt(0)
	s_setprio 1
	s_waitcnt lgkmcnt(0)
	v_mfma_f32_16x16x32_bf16 v[120:123], v[176:179], v[144:147], v[120:123]
	v_mfma_f32_16x16x32_bf16 v[112:115], v[200:203], v[144:147], v[112:115]
	v_mfma_f32_16x16x32_bf16 v[104:107], v[176:179], v[152:155], v[104:107]
	v_mfma_f32_16x16x32_bf16 v[96:99], v[200:203], v[152:155], v[96:99]
	v_mfma_f32_16x16x32_bf16 v[88:91], v[176:179], v[160:163], v[88:91]
	v_mfma_f32_16x16x32_bf16 v[80:83], v[200:203], v[160:163], v[80:83]
	v_mfma_f32_16x16x32_bf16 v[72:75], v[176:179], v[168:171], v[72:75]
	v_mfma_f32_16x16x32_bf16 v[64:67], v[200:203], v[168:171], v[64:67]
	v_mfma_f32_16x16x32_bf16 v[120:123], v[196:199], v[148:151], v[120:123]
	v_mfma_f32_16x16x32_bf16 v[112:115], v[204:207], v[148:151], v[112:115]
	v_mfma_f32_16x16x32_bf16 v[104:107], v[196:199], v[156:159], v[104:107]
	v_mfma_f32_16x16x32_bf16 v[96:99], v[204:207], v[156:159], v[96:99]
	v_mfma_f32_16x16x32_bf16 v[88:91], v[196:199], v[164:167], v[88:91]
	v_mfma_f32_16x16x32_bf16 v[80:83], v[204:207], v[164:167], v[80:83]
	v_mfma_f32_16x16x32_bf16 v[72:75], v[196:199], v[172:175], v[72:75]
	v_mfma_f32_16x16x32_bf16 v[64:67], v[204:207], v[172:175], v[64:67]
	s_setprio 0
	s_mov_b32 m0, s8
	v_lshl_add_u64 v[208:209], v[212:213], 0, s[96:97]
	s_barrier
	s_nop 0
	ds_read_b128 v[144:147], v239 offset:49152
	ds_read_b128 v[148:151], v239 offset:50176
	ds_read_b128 v[152:155], v239 offset:51200
	ds_read_b128 v[156:159], v239 offset:52224
	ds_read_b128 v[160:163], v239 offset:53248
	ds_read_b128 v[164:167], v239 offset:54272
	ds_read_b128 v[168:171], v239 offset:55296
	ds_read_b128 v[172:175], v239 offset:56320
	global_load_lds_dwordx4 v[208:209], off
	v_lshl_add_u64 v[208:209], v[214:215], 0, s[96:97]
	s_mov_b32 m0, s9
	s_nop 0
	global_load_lds_dwordx4 v[208:209], off
	s_barrier
	s_waitcnt lgkmcnt(0)
	s_setprio 1
	s_waitcnt lgkmcnt(0)
	v_mfma_f32_16x16x32_bf16 v[60:63], v[128:131], v[144:147], v[60:63]
	v_mfma_f32_16x16x32_bf16 v[52:55], v[136:139], v[144:147], v[52:55]
	v_mfma_f32_16x16x32_bf16 v[44:47], v[128:131], v[152:155], v[44:47]
	v_mfma_f32_16x16x32_bf16 v[36:39], v[136:139], v[152:155], v[36:39]
	v_mfma_f32_16x16x32_bf16 v[28:31], v[128:131], v[160:163], v[28:31]
	v_mfma_f32_16x16x32_bf16 v[20:23], v[136:139], v[160:163], v[20:23]
	v_mfma_f32_16x16x32_bf16 v[12:15], v[128:131], v[168:171], v[12:15]
	v_mfma_f32_16x16x32_bf16 v[4:7], v[136:139], v[168:171], v[4:7]
	v_mfma_f32_16x16x32_bf16 v[60:63], v[132:135], v[148:151], v[60:63]
	v_mfma_f32_16x16x32_bf16 v[52:55], v[140:143], v[148:151], v[52:55]
	v_mfma_f32_16x16x32_bf16 v[44:47], v[132:135], v[156:159], v[44:47]
	v_mfma_f32_16x16x32_bf16 v[36:39], v[140:143], v[156:159], v[36:39]
	v_mfma_f32_16x16x32_bf16 v[28:31], v[132:135], v[164:167], v[28:31]
	v_mfma_f32_16x16x32_bf16 v[20:23], v[140:143], v[164:167], v[20:23]
	v_mfma_f32_16x16x32_bf16 v[12:15], v[132:135], v[172:175], v[12:15]
	v_mfma_f32_16x16x32_bf16 v[4:7], v[140:143], v[172:175], v[4:7]
	s_setprio 0
	s_barrier
	s_add_i32 s40, s40, s33
	s_nop 0
	v_lshl_add_u64 v[128:129], v[216:217], 0, s[96:97]
	s_mov_b32 m0, s40
	s_nop 0
	global_load_lds_dwordx4 v[128:129], off
	v_lshl_add_u64 v[128:129], v[218:219], 0, s[96:97]
	s_add_i32 m0, s40, 0x2000
	s_nop 0
	s_nop 0
	global_load_lds_dwordx4 v[128:129], off
	s_waitcnt vmcnt(6)
	s_barrier
	s_setprio 1
	s_nop 0
	v_mfma_f32_16x16x32_bf16 v[56:59], v[176:179], v[144:147], v[56:59]
	v_mfma_f32_16x16x32_bf16 v[48:51], v[200:203], v[144:147], v[48:51]
	v_mfma_f32_16x16x32_bf16 v[40:43], v[176:179], v[152:155], v[40:43]
	v_mfma_f32_16x16x32_bf16 v[32:35], v[200:203], v[152:155], v[32:35]
	v_mfma_f32_16x16x32_bf16 v[24:27], v[176:179], v[160:163], v[24:27]
	v_mfma_f32_16x16x32_bf16 v[16:19], v[200:203], v[160:163], v[16:19]
	v_mfma_f32_16x16x32_bf16 v[8:11], v[176:179], v[168:171], v[8:11]
	v_mfma_f32_16x16x32_bf16 v[0:3], v[200:203], v[168:171], v[0:3]
	v_mfma_f32_16x16x32_bf16 v[56:59], v[196:199], v[148:151], v[56:59]
	v_mfma_f32_16x16x32_bf16 v[48:51], v[204:207], v[148:151], v[48:51]
	v_mfma_f32_16x16x32_bf16 v[40:43], v[196:199], v[156:159], v[40:43]
	v_mfma_f32_16x16x32_bf16 v[32:35], v[204:207], v[156:159], v[32:35]
	v_mfma_f32_16x16x32_bf16 v[24:27], v[196:199], v[164:167], v[24:27]
	v_mfma_f32_16x16x32_bf16 v[16:19], v[204:207], v[164:167], v[16:19]
	v_mfma_f32_16x16x32_bf16 v[8:11], v[196:199], v[172:175], v[8:11]
	v_mfma_f32_16x16x32_bf16 v[0:3], v[204:207], v[172:175], v[0:3]
	s_setprio 0
	s_nop 0
	s_add_u32 s0, s0, 0x100
	s_addc_u32 s1, s1, 0
	s_nop 0
	s_add_u32 s70, s70, 0x100
	s_addc_u32 s71, s71, 0
	s_cmp_ge_u32 s72, s7
	s_mov_b32 s40, s72
	s_barrier
	s_cbranch_scc0 .LBB0_141
	v_lshl_add_u32 v196, s19, 8, v181
	s_cmp_lt_i32 s78, 2
	s_mov_b64 s[0:1], -1
	s_cbranch_scc1 .LBB0_223
	s_cmp_gt_i32 s78, 2
	s_cbranch_scc0 .LBB0_220
	s_lshl_b32 s0, s18, 8
	s_ashr_i32 s68, s18, 1
	s_and_b32 s0, s0, 0x100
	s_cmp_lt_i32 s68, 2
	v_or_b32_e32 v148, s0, v238
	s_cselect_b64 s[0:1], -1, 0
	s_lshl_b32 s40, s68, 9
	s_add_i32 s80, s40, 0xfffffc00
	v_readlane_b32 s48, v241, 0
	s_lshl_b64 s[70:71], s[80:81], 2
	v_readlane_b32 s62, v241, 14
	v_readlane_b32 s63, v241, 15
	s_add_u32 s69, s62, s70
	s_addc_u32 s80, s63, s71
	s_ashr_i32 s41, s40, 31
	v_readlane_b32 s58, v241, 10
	s_lshl_b64 s[40:41], s[40:41], 2
	v_readlane_b32 s59, v241, 11
	s_add_u32 s99, s58, s40
	s_mov_b32 s83, s82
	s_addc_u32 s82, s59, s41
	s_cmp_lt_i32 s68, 4
	s_cselect_b64 s[72:73], -1, 0
	s_cmp_gt_i32 s68, 3
	s_cselect_b64 s[70:71], -1, 0
	v_mov_b32_e32 v132, 0
	s_and_b64 vcc, exec, s[70:71]
	v_lshlrev_b32_e32 v136, 2, v148
	v_mov_b32_e32 v140, 0
	v_mov_b32_e32 v141, v132
	v_mov_b32_e32 v142, 0
	v_mov_b32_e32 v143, 0
	v_readlane_b32 s49, v241, 1
	v_readlane_b32 s50, v241, 2
	v_readlane_b32 s51, v241, 3
	v_readlane_b32 s52, v241, 4
	v_readlane_b32 s53, v241, 5
	v_readlane_b32 s54, v241, 6
	v_readlane_b32 s55, v241, 7
	v_readlane_b32 s56, v241, 8
	v_readlane_b32 s57, v241, 9
	v_readlane_b32 s60, v241, 12
	v_readlane_b32 s61, v241, 13
	s_cbranch_vccnz .LBB0_146
	s_and_b64 s[40:41], s[0:1], exec
	s_cselect_b32 s41, s82, s80
	s_cselect_b32 s40, s99, s69
	global_load_dwordx4 v[140:143], v136, s[40:41]
